# write-through (sc1) stores for the SwiGLU output tile in the hand-written gate/up epilogue (nothing dirty to write back at the following grid barrier)
# baseline (speedup 1.0000x reference)
; __device__ __forceinline__ unsigned cvt_pk_bf16(float lo, float hi) { unsigned r; asm volatile("v_cvt_pk_bf16_f32 %0, %1, %2" : "=v"(r) : "v"(lo), "v"(hi)); return r; }
;     __device__ __forceinline__ float silu(float x) const { return x * __builtin_amdgcn_rcpf(1.0f + __builtin_amdgcn_exp2f(-x * kLog2e)); }
;     __device__ __forceinline__ void operator()(const f32x4 (&acc)[2][2][4][2], const Unit& u, int wr, int wc, int fr, int fq) const {
;     ...
;             for (int m = 0; m < 4; ++m) {
;                 const int row = row0 + ai * HALF + m * 16;
;                 const float r = __builtin_amdgcn_rsqf(rr[ai][m] * (1.0f / 1024.0f) + 1e-6f);
;                 const f32x4 g0 = acc[ai][0][m][0] * r + bg0, g1 = acc[ai][0][m][1] * r + bg1, u0 = acc[ai][1][m][0] * r + bu0, u1 = acc[ai][1][m][1] * r + bu1;
;                 u32x4 w; w.x = cvt_pk_bf16(silu(g0[0]) * u0[0], silu(g0[1]) * u0[1]); w.y = cvt_pk_bf16(silu(g0[2]) * u0[2], silu(g0[3]) * u0[3]);
;                 w.z = cvt_pk_bf16(silu(g1[0]) * u1[0], silu(g1[1]) * u1[1]); w.w = cvt_pk_bf16(silu(g1[2]) * u1[2], silu(g1[3]) * u1[3]);
;                 *(u32x4*)(Aout + (size_t)row * 2816 + col0) = w;
.LBB0_67:
	s_bitcmp1_b32 s27, 0
	s_cselect_b32 s2, 0x1400, 0
	s_add_i32 s2, s2, 0x20000
	s_lshl_b32 s3, s69, 2
	s_add_i32 s3, s2, s3
	v_lshl_add_u32 v158, v161, 2, s3
	v_add_u32_e32 v159, s2, v163
	ds_read_b128 v[176:179], v159
	ds_read_b128 v[78:81], v158 offset:4096
	ds_read_b128 v[70:73], v158 offset:4112
	ds_read_b128 v[66:69], v158 offset:4608
	ds_read_b128 v[62:65], v158 offset:4624
	v_lshl_or_b32 v167, s60, 7, v164
	v_lshl_add_u32 v169, s61, 8, v160
	v_lshlrev_b32_e32 v167, 1, v167
	v_mad_u32_u24 v167, v169, s54, v167
	s_mov_b32 s2, 0xbfb8aa3b
	s_mov_b32 s3, 1.0
	s_waitcnt lgkmcnt(0)
	v_add_f32_e32 v168, v176, v177
	v_add_f32_e32 v169, v178, v179
	v_add_f32_e32 v168, v168, v169
	v_fmamk_f32 v168, v168, 0x3a800000, v225
	v_rsq_f32_e32 v168, v168
	ds_read_b128 v[176:179], v159 offset:256
	v_pk_fma_f32 v[142:143], v[142:143], v[168:169], v[78:79] op_sel_hi:[1,0,1]
	v_pk_fma_f32 v[144:145], v[144:145], v[168:169], v[80:81] op_sel_hi:[1,0,1]
	v_pk_fma_f32 v[138:139], v[138:139], v[168:169], v[70:71] op_sel_hi:[1,0,1]
	v_pk_fma_f32 v[140:141], v[140:141], v[168:169], v[72:73] op_sel_hi:[1,0,1]
	v_pk_fma_f32 v[134:135], v[134:135], v[168:169], v[66:67] op_sel_hi:[1,0,1]
	v_pk_fma_f32 v[136:137], v[136:137], v[168:169], v[68:69] op_sel_hi:[1,0,1]
	v_pk_fma_f32 v[130:131], v[130:131], v[168:169], v[62:63] op_sel_hi:[1,0,1]
	v_pk_fma_f32 v[132:133], v[132:133], v[168:169], v[64:65] op_sel_hi:[1,0,1]
	v_pk_mul_f32 v[170:171], v[142:143], s[2:3] op_sel_hi:[1,0]
	v_pk_mul_f32 v[172:173], v[144:145], s[2:3] op_sel_hi:[1,0]
	v_pk_mul_f32 v[174:175], v[138:139], s[2:3] op_sel_hi:[1,0]
	v_pk_mul_f32 v[180:181], v[140:141], s[2:3] op_sel_hi:[1,0]
	v_exp_f32_e32 v170, v170
	v_exp_f32_e32 v171, v171
	v_exp_f32_e32 v172, v172
	v_exp_f32_e32 v173, v173
	v_exp_f32_e32 v174, v174
	v_exp_f32_e32 v175, v175
	v_exp_f32_e32 v180, v180
	v_exp_f32_e32 v181, v181
	v_pk_add_f32 v[170:171], v[170:171], s[2:3] op_sel:[0,1] op_sel_hi:[1,1]
	v_pk_add_f32 v[172:173], v[172:173], s[2:3] op_sel:[0,1] op_sel_hi:[1,1]
	v_pk_add_f32 v[174:175], v[174:175], s[2:3] op_sel:[0,1] op_sel_hi:[1,1]
	v_pk_add_f32 v[180:181], v[180:181], s[2:3] op_sel:[0,1] op_sel_hi:[1,1]
	v_rcp_f32_e32 v170, v170
	v_rcp_f32_e32 v171, v171
	v_rcp_f32_e32 v172, v172
	v_rcp_f32_e32 v173, v173
	v_rcp_f32_e32 v174, v174
	v_rcp_f32_e32 v175, v175
	v_rcp_f32_e32 v180, v180
	v_rcp_f32_e32 v181, v181
	v_pk_mul_f32 v[142:143], v[142:143], v[170:171]
	v_pk_mul_f32 v[144:145], v[144:145], v[172:173]
	v_pk_mul_f32 v[138:139], v[138:139], v[174:175]
	v_pk_mul_f32 v[140:141], v[140:141], v[180:181]
	v_pk_mul_f32 v[142:143], v[134:135], v[142:143]
	v_pk_mul_f32 v[144:145], v[136:137], v[144:145]
	v_pk_mul_f32 v[138:139], v[130:131], v[138:139]
	v_pk_mul_f32 v[140:141], v[132:133], v[140:141]
	v_cvt_pk_bf16_f32 v130, v142, v143
	v_cvt_pk_bf16_f32 v131, v144, v145
	v_cvt_pk_bf16_f32 v132, v138, v139
	v_cvt_pk_bf16_f32 v133, v140, v141
	global_store_dwordx4 v167, v[130:133], s[84:85] sc1
	s_waitcnt lgkmcnt(0)
	v_add_f32_e32 v168, v176, v177
	v_add_f32_e32 v169, v178, v179
	v_add_f32_e32 v168, v168, v169
	v_fmamk_f32 v168, v168, 0x3a800000, v225
	v_rsq_f32_e32 v168, v168
	ds_read_b128 v[176:179], v159 offset:512
	v_pk_fma_f32 v[126:127], v[126:127], v[168:169], v[78:79] op_sel_hi:[1,0,1]
	v_pk_fma_f32 v[128:129], v[128:129], v[168:169], v[80:81] op_sel_hi:[1,0,1]
	v_pk_fma_f32 v[122:123], v[122:123], v[168:169], v[70:71] op_sel_hi:[1,0,1]
	v_pk_fma_f32 v[124:125], v[124:125], v[168:169], v[72:73] op_sel_hi:[1,0,1]
	v_pk_fma_f32 v[118:119], v[118:119], v[168:169], v[66:67] op_sel_hi:[1,0,1]
	v_pk_fma_f32 v[120:121], v[120:121], v[168:169], v[68:69] op_sel_hi:[1,0,1]
	v_pk_fma_f32 v[114:115], v[114:115], v[168:169], v[62:63] op_sel_hi:[1,0,1]
	v_pk_fma_f32 v[116:117], v[116:117], v[168:169], v[64:65] op_sel_hi:[1,0,1]
	v_pk_mul_f32 v[170:171], v[126:127], s[2:3] op_sel_hi:[1,0]
	v_pk_mul_f32 v[172:173], v[128:129], s[2:3] op_sel_hi:[1,0]
	v_pk_mul_f32 v[174:175], v[122:123], s[2:3] op_sel_hi:[1,0]
	v_pk_mul_f32 v[180:181], v[124:125], s[2:3] op_sel_hi:[1,0]
	v_exp_f32_e32 v170, v170
	v_exp_f32_e32 v171, v171
	v_exp_f32_e32 v172, v172
	v_exp_f32_e32 v173, v173
	v_exp_f32_e32 v174, v174
	v_exp_f32_e32 v175, v175
	v_exp_f32_e32 v180, v180
	v_exp_f32_e32 v181, v181
	v_pk_add_f32 v[170:171], v[170:171], s[2:3] op_sel:[0,1] op_sel_hi:[1,1]
	v_pk_add_f32 v[172:173], v[172:173], s[2:3] op_sel:[0,1] op_sel_hi:[1,1]
	v_pk_add_f32 v[174:175], v[174:175], s[2:3] op_sel:[0,1] op_sel_hi:[1,1]
	v_pk_add_f32 v[180:181], v[180:181], s[2:3] op_sel:[0,1] op_sel_hi:[1,1]
	v_rcp_f32_e32 v170, v170
	v_rcp_f32_e32 v171, v171
	v_rcp_f32_e32 v172, v172
	v_rcp_f32_e32 v173, v173
	v_rcp_f32_e32 v174, v174
	v_rcp_f32_e32 v175, v175
	v_rcp_f32_e32 v180, v180
	v_rcp_f32_e32 v181, v181
	v_pk_mul_f32 v[126:127], v[126:127], v[170:171]
	v_pk_mul_f32 v[128:129], v[128:129], v[172:173]
	v_pk_mul_f32 v[122:123], v[122:123], v[174:175]
	v_pk_mul_f32 v[124:125], v[124:125], v[180:181]
	v_pk_mul_f32 v[126:127], v[118:119], v[126:127]
	v_pk_mul_f32 v[128:129], v[120:121], v[128:129]
	v_pk_mul_f32 v[122:123], v[114:115], v[122:123]
	v_pk_mul_f32 v[124:125], v[116:117], v[124:125]
	v_add_u32_e32 v158, 0x16000, v167
	v_cvt_pk_bf16_f32 v114, v126, v127
	v_cvt_pk_bf16_f32 v115, v128, v129
	v_cvt_pk_bf16_f32 v116, v122, v123
	v_cvt_pk_bf16_f32 v117, v124, v125
	global_store_dwordx4 v158, v[114:117], s[84:85] sc1
	s_waitcnt lgkmcnt(0)
; __device__ __forceinline__ unsigned cvt_pk_bf16(float lo, float hi) { unsigned r; asm volatile("v_cvt_pk_bf16_f32 %0, %1, %2" : "=v"(r) : "v"(lo), "v"(hi)); return r; }
;     __device__ __forceinline__ float silu(float x) const { return x * __builtin_amdgcn_rcpf(1.0f + __builtin_amdgcn_exp2f(-x * kLog2e)); }
;     __device__ __forceinline__ void operator()(const f32x4 (&acc)[2][2][4][2], const Unit& u, int wr, int wc, int fr, int fq) const {
;     ...
;             for (int m = 0; m < 4; ++m) {
;                 const int row = row0 + ai * HALF + m * 16;
;                 const float r = __builtin_amdgcn_rsqf(rr[ai][m] * (1.0f / 1024.0f) + 1e-6f);
;                 const f32x4 g0 = acc[ai][0][m][0] * r + bg0, g1 = acc[ai][0][m][1] * r + bg1, u0 = acc[ai][1][m][0] * r + bu0, u1 = acc[ai][1][m][1] * r + bu1;
;                 u32x4 w; w.x = cvt_pk_bf16(silu(g0[0]) * u0[0], silu(g0[1]) * u0[1]); w.y = cvt_pk_bf16(silu(g0[2]) * u0[2], silu(g0[3]) * u0[3]);
;                 w.z = cvt_pk_bf16(silu(g1[0]) * u1[0], silu(g1[1]) * u1[1]); w.w = cvt_pk_bf16(silu(g1[2]) * u1[2], silu(g1[3]) * u1[3]);
;                 *(u32x4*)(Aout + (size_t)row * 2816 + col0) = w;
	v_add_f32_e32 v168, v176, v177
	v_add_f32_e32 v169, v178, v179
	v_add_f32_e32 v168, v168, v169
	v_fmamk_f32 v168, v168, 0x3a800000, v225
	v_rsq_f32_e32 v168, v168
	ds_read_b128 v[176:179], v159 offset:768
	v_pk_fma_f32 v[110:111], v[110:111], v[168:169], v[78:79] op_sel_hi:[1,0,1]
	v_pk_fma_f32 v[112:113], v[112:113], v[168:169], v[80:81] op_sel_hi:[1,0,1]
	v_pk_fma_f32 v[106:107], v[106:107], v[168:169], v[70:71] op_sel_hi:[1,0,1]
	v_pk_fma_f32 v[108:109], v[108:109], v[168:169], v[72:73] op_sel_hi:[1,0,1]
	v_pk_fma_f32 v[102:103], v[102:103], v[168:169], v[66:67] op_sel_hi:[1,0,1]
	v_pk_fma_f32 v[104:105], v[104:105], v[168:169], v[68:69] op_sel_hi:[1,0,1]
	v_pk_fma_f32 v[98:99], v[98:99], v[168:169], v[62:63] op_sel_hi:[1,0,1]
	v_pk_fma_f32 v[100:101], v[100:101], v[168:169], v[64:65] op_sel_hi:[1,0,1]
	v_pk_mul_f32 v[170:171], v[110:111], s[2:3] op_sel_hi:[1,0]
	v_pk_mul_f32 v[172:173], v[112:113], s[2:3] op_sel_hi:[1,0]
	v_pk_mul_f32 v[174:175], v[106:107], s[2:3] op_sel_hi:[1,0]
	v_pk_mul_f32 v[180:181], v[108:109], s[2:3] op_sel_hi:[1,0]
	v_exp_f32_e32 v170, v170
	v_exp_f32_e32 v171, v171
	v_exp_f32_e32 v172, v172
	v_exp_f32_e32 v173, v173
	v_exp_f32_e32 v174, v174
	v_exp_f32_e32 v175, v175
	v_exp_f32_e32 v180, v180
	v_exp_f32_e32 v181, v181
	v_pk_add_f32 v[170:171], v[170:171], s[2:3] op_sel:[0,1] op_sel_hi:[1,1]
	v_pk_add_f32 v[172:173], v[172:173], s[2:3] op_sel:[0,1] op_sel_hi:[1,1]
	v_pk_add_f32 v[174:175], v[174:175], s[2:3] op_sel:[0,1] op_sel_hi:[1,1]
	v_pk_add_f32 v[180:181], v[180:181], s[2:3] op_sel:[0,1] op_sel_hi:[1,1]
	v_rcp_f32_e32 v170, v170
	v_rcp_f32_e32 v171, v171
	v_rcp_f32_e32 v172, v172
	v_rcp_f32_e32 v173, v173
	v_rcp_f32_e32 v174, v174
	v_rcp_f32_e32 v175, v175
	v_rcp_f32_e32 v180, v180
	v_rcp_f32_e32 v181, v181
	v_pk_mul_f32 v[110:111], v[110:111], v[170:171]
	v_pk_mul_f32 v[112:113], v[112:113], v[172:173]
	v_pk_mul_f32 v[106:107], v[106:107], v[174:175]
	v_pk_mul_f32 v[108:109], v[108:109], v[180:181]
	v_pk_mul_f32 v[110:111], v[102:103], v[110:111]
	v_pk_mul_f32 v[112:113], v[104:105], v[112:113]
	v_pk_mul_f32 v[106:107], v[98:99], v[106:107]
	v_pk_mul_f32 v[108:109], v[100:101], v[108:109]
	v_add_u32_e32 v158, 0x2c000, v167
	v_cvt_pk_bf16_f32 v98, v110, v111
	v_cvt_pk_bf16_f32 v99, v112, v113
	v_cvt_pk_bf16_f32 v100, v106, v107
	v_cvt_pk_bf16_f32 v101, v108, v109
	global_store_dwordx4 v158, v[98:101], s[84:85] sc1
	s_waitcnt lgkmcnt(0)
	v_add_f32_e32 v168, v176, v177
	v_add_f32_e32 v169, v178, v179
	v_add_f32_e32 v168, v168, v169
	v_fmamk_f32 v168, v168, 0x3a800000, v225
	v_rsq_f32_e32 v168, v168
	ds_read_b128 v[176:179], v159 offset:2048
	v_pk_fma_f32 v[94:95], v[94:95], v[168:169], v[78:79] op_sel_hi:[1,0,1]
	v_pk_fma_f32 v[96:97], v[96:97], v[168:169], v[80:81] op_sel_hi:[1,0,1]
	v_pk_fma_f32 v[90:91], v[90:91], v[168:169], v[70:71] op_sel_hi:[1,0,1]
	v_pk_fma_f32 v[92:93], v[92:93], v[168:169], v[72:73] op_sel_hi:[1,0,1]
	v_pk_fma_f32 v[86:87], v[86:87], v[168:169], v[66:67] op_sel_hi:[1,0,1]
	v_pk_fma_f32 v[88:89], v[88:89], v[168:169], v[68:69] op_sel_hi:[1,0,1]
	v_pk_fma_f32 v[82:83], v[82:83], v[168:169], v[62:63] op_sel_hi:[1,0,1]
	v_pk_fma_f32 v[84:85], v[84:85], v[168:169], v[64:65] op_sel_hi:[1,0,1]
	v_pk_mul_f32 v[170:171], v[94:95], s[2:3] op_sel_hi:[1,0]
	v_pk_mul_f32 v[172:173], v[96:97], s[2:3] op_sel_hi:[1,0]
	v_pk_mul_f32 v[174:175], v[90:91], s[2:3] op_sel_hi:[1,0]
	v_pk_mul_f32 v[180:181], v[92:93], s[2:3] op_sel_hi:[1,0]
	v_exp_f32_e32 v170, v170
	v_exp_f32_e32 v171, v171
	v_exp_f32_e32 v172, v172
	v_exp_f32_e32 v173, v173
	v_exp_f32_e32 v174, v174
	v_exp_f32_e32 v175, v175
	v_exp_f32_e32 v180, v180
	v_exp_f32_e32 v181, v181
	v_pk_add_f32 v[170:171], v[170:171], s[2:3] op_sel:[0,1] op_sel_hi:[1,1]
	v_pk_add_f32 v[172:173], v[172:173], s[2:3] op_sel:[0,1] op_sel_hi:[1,1]
	v_pk_add_f32 v[174:175], v[174:175], s[2:3] op_sel:[0,1] op_sel_hi:[1,1]
	v_pk_add_f32 v[180:181], v[180:181], s[2:3] op_sel:[0,1] op_sel_hi:[1,1]
	v_rcp_f32_e32 v170, v170
	v_rcp_f32_e32 v171, v171
	v_rcp_f32_e32 v172, v172
	v_rcp_f32_e32 v173, v173
	v_rcp_f32_e32 v174, v174
	v_rcp_f32_e32 v175, v175
	v_rcp_f32_e32 v180, v180
	v_rcp_f32_e32 v181, v181
	v_pk_mul_f32 v[94:95], v[94:95], v[170:171]
	v_pk_mul_f32 v[96:97], v[96:97], v[172:173]
	v_pk_mul_f32 v[90:91], v[90:91], v[174:175]
	v_pk_mul_f32 v[92:93], v[92:93], v[180:181]
	v_pk_mul_f32 v[94:95], v[86:87], v[94:95]
	v_pk_mul_f32 v[96:97], v[88:89], v[96:97]
	v_pk_mul_f32 v[90:91], v[82:83], v[90:91]
	v_pk_mul_f32 v[92:93], v[84:85], v[92:93]
	v_add_u32_e32 v158, 0x42000, v167
	v_cvt_pk_bf16_f32 v82, v94, v95
	v_cvt_pk_bf16_f32 v83, v96, v97
	v_cvt_pk_bf16_f32 v84, v90, v91
	v_cvt_pk_bf16_f32 v85, v92, v93
	global_store_dwordx4 v158, v[82:85], s[84:85] sc1
	s_waitcnt lgkmcnt(0)
; __device__ __forceinline__ unsigned cvt_pk_bf16(float lo, float hi) { unsigned r; asm volatile("v_cvt_pk_bf16_f32 %0, %1, %2" : "=v"(r) : "v"(lo), "v"(hi)); return r; }
;     __device__ __forceinline__ float silu(float x) const { return x * __builtin_amdgcn_rcpf(1.0f + __builtin_amdgcn_exp2f(-x * kLog2e)); }
;     __device__ __forceinline__ void operator()(const f32x4 (&acc)[2][2][4][2], const Unit& u, int wr, int wc, int fr, int fq) const {
;     ...
;             for (int m = 0; m < 4; ++m) {
;                 const int row = row0 + ai * HALF + m * 16;
;                 const float r = __builtin_amdgcn_rsqf(rr[ai][m] * (1.0f / 1024.0f) + 1e-6f);
;                 const f32x4 g0 = acc[ai][0][m][0] * r + bg0, g1 = acc[ai][0][m][1] * r + bg1, u0 = acc[ai][1][m][0] * r + bu0, u1 = acc[ai][1][m][1] * r + bu1;
;                 u32x4 w; w.x = cvt_pk_bf16(silu(g0[0]) * u0[0], silu(g0[1]) * u0[1]); w.y = cvt_pk_bf16(silu(g0[2]) * u0[2], silu(g0[3]) * u0[3]);
;                 w.z = cvt_pk_bf16(silu(g1[0]) * u1[0], silu(g1[1]) * u1[1]); w.w = cvt_pk_bf16(silu(g1[2]) * u1[2], silu(g1[3]) * u1[3]);
;                 *(u32x4*)(Aout + (size_t)row * 2816 + col0) = w;
	v_add_f32_e32 v168, v176, v177
	v_add_f32_e32 v169, v178, v179
	v_add_f32_e32 v168, v168, v169
	v_fmamk_f32 v168, v168, 0x3a800000, v225
	v_rsq_f32_e32 v168, v168
	ds_read_b128 v[176:179], v159 offset:2304
	v_pk_fma_f32 v[74:75], v[74:75], v[168:169], v[78:79] op_sel_hi:[1,0,1]
	v_pk_fma_f32 v[76:77], v[76:77], v[168:169], v[80:81] op_sel_hi:[1,0,1]
	v_pk_fma_f32 v[58:59], v[58:59], v[168:169], v[70:71] op_sel_hi:[1,0,1]
	v_pk_fma_f32 v[60:61], v[60:61], v[168:169], v[72:73] op_sel_hi:[1,0,1]
	v_pk_fma_f32 v[54:55], v[54:55], v[168:169], v[66:67] op_sel_hi:[1,0,1]
	v_pk_fma_f32 v[56:57], v[56:57], v[168:169], v[68:69] op_sel_hi:[1,0,1]
	v_pk_fma_f32 v[50:51], v[50:51], v[168:169], v[62:63] op_sel_hi:[1,0,1]
	v_pk_fma_f32 v[52:53], v[52:53], v[168:169], v[64:65] op_sel_hi:[1,0,1]
	v_pk_mul_f32 v[170:171], v[74:75], s[2:3] op_sel_hi:[1,0]
	v_pk_mul_f32 v[172:173], v[76:77], s[2:3] op_sel_hi:[1,0]
	v_pk_mul_f32 v[174:175], v[58:59], s[2:3] op_sel_hi:[1,0]
	v_pk_mul_f32 v[180:181], v[60:61], s[2:3] op_sel_hi:[1,0]
	v_exp_f32_e32 v170, v170
	v_exp_f32_e32 v171, v171
	v_exp_f32_e32 v172, v172
	v_exp_f32_e32 v173, v173
	v_exp_f32_e32 v174, v174
	v_exp_f32_e32 v175, v175
	v_exp_f32_e32 v180, v180
	v_exp_f32_e32 v181, v181
	v_pk_add_f32 v[170:171], v[170:171], s[2:3] op_sel:[0,1] op_sel_hi:[1,1]
	v_pk_add_f32 v[172:173], v[172:173], s[2:3] op_sel:[0,1] op_sel_hi:[1,1]
	v_pk_add_f32 v[174:175], v[174:175], s[2:3] op_sel:[0,1] op_sel_hi:[1,1]
	v_pk_add_f32 v[180:181], v[180:181], s[2:3] op_sel:[0,1] op_sel_hi:[1,1]
	v_rcp_f32_e32 v170, v170
	v_rcp_f32_e32 v171, v171
	v_rcp_f32_e32 v172, v172
	v_rcp_f32_e32 v173, v173
	v_rcp_f32_e32 v174, v174
	v_rcp_f32_e32 v175, v175
	v_rcp_f32_e32 v180, v180
	v_rcp_f32_e32 v181, v181
	v_pk_mul_f32 v[74:75], v[74:75], v[170:171]
	v_pk_mul_f32 v[76:77], v[76:77], v[172:173]
	v_pk_mul_f32 v[58:59], v[58:59], v[174:175]
	v_pk_mul_f32 v[60:61], v[60:61], v[180:181]
	v_pk_mul_f32 v[74:75], v[54:55], v[74:75]
	v_pk_mul_f32 v[76:77], v[56:57], v[76:77]
	v_pk_mul_f32 v[58:59], v[50:51], v[58:59]
	v_pk_mul_f32 v[60:61], v[52:53], v[60:61]
	v_add_u32_e32 v158, 0xb0000, v167
	v_cvt_pk_bf16_f32 v50, v74, v75
	v_cvt_pk_bf16_f32 v51, v76, v77
	v_cvt_pk_bf16_f32 v52, v58, v59
	v_cvt_pk_bf16_f32 v53, v60, v61
	global_store_dwordx4 v158, v[50:53], s[84:85] sc1
	s_waitcnt lgkmcnt(0)
	v_add_f32_e32 v168, v176, v177
	v_add_f32_e32 v169, v178, v179
	v_add_f32_e32 v168, v168, v169
	v_fmamk_f32 v168, v168, 0x3a800000, v225
	v_rsq_f32_e32 v168, v168
	ds_read_b128 v[176:179], v159 offset:2560
	v_pk_fma_f32 v[46:47], v[46:47], v[168:169], v[78:79] op_sel_hi:[1,0,1]
	v_pk_fma_f32 v[48:49], v[48:49], v[168:169], v[80:81] op_sel_hi:[1,0,1]
	v_pk_fma_f32 v[42:43], v[42:43], v[168:169], v[70:71] op_sel_hi:[1,0,1]
	v_pk_fma_f32 v[44:45], v[44:45], v[168:169], v[72:73] op_sel_hi:[1,0,1]
	v_pk_fma_f32 v[38:39], v[38:39], v[168:169], v[66:67] op_sel_hi:[1,0,1]
	v_pk_fma_f32 v[40:41], v[40:41], v[168:169], v[68:69] op_sel_hi:[1,0,1]
	v_pk_fma_f32 v[34:35], v[34:35], v[168:169], v[62:63] op_sel_hi:[1,0,1]
	v_pk_fma_f32 v[36:37], v[36:37], v[168:169], v[64:65] op_sel_hi:[1,0,1]
	v_pk_mul_f32 v[170:171], v[46:47], s[2:3] op_sel_hi:[1,0]
	v_pk_mul_f32 v[172:173], v[48:49], s[2:3] op_sel_hi:[1,0]
	v_pk_mul_f32 v[174:175], v[42:43], s[2:3] op_sel_hi:[1,0]
	v_pk_mul_f32 v[180:181], v[44:45], s[2:3] op_sel_hi:[1,0]
	v_exp_f32_e32 v170, v170
	v_exp_f32_e32 v171, v171
	v_exp_f32_e32 v172, v172
	v_exp_f32_e32 v173, v173
	v_exp_f32_e32 v174, v174
	v_exp_f32_e32 v175, v175
	v_exp_f32_e32 v180, v180
	v_exp_f32_e32 v181, v181
	v_pk_add_f32 v[170:171], v[170:171], s[2:3] op_sel:[0,1] op_sel_hi:[1,1]
	v_pk_add_f32 v[172:173], v[172:173], s[2:3] op_sel:[0,1] op_sel_hi:[1,1]
	v_pk_add_f32 v[174:175], v[174:175], s[2:3] op_sel:[0,1] op_sel_hi:[1,1]
	v_pk_add_f32 v[180:181], v[180:181], s[2:3] op_sel:[0,1] op_sel_hi:[1,1]
	v_rcp_f32_e32 v170, v170
	v_rcp_f32_e32 v171, v171
	v_rcp_f32_e32 v172, v172
	v_rcp_f32_e32 v173, v173
	v_rcp_f32_e32 v174, v174
	v_rcp_f32_e32 v175, v175
	v_rcp_f32_e32 v180, v180
	v_rcp_f32_e32 v181, v181
	v_pk_mul_f32 v[46:47], v[46:47], v[170:171]
	v_pk_mul_f32 v[48:49], v[48:49], v[172:173]
	v_pk_mul_f32 v[42:43], v[42:43], v[174:175]
	v_pk_mul_f32 v[44:45], v[44:45], v[180:181]
	v_pk_mul_f32 v[46:47], v[38:39], v[46:47]
	v_pk_mul_f32 v[48:49], v[40:41], v[48:49]
	v_pk_mul_f32 v[42:43], v[34:35], v[42:43]
	v_pk_mul_f32 v[44:45], v[36:37], v[44:45]
	v_add_u32_e32 v158, 0xc6000, v167
	v_cvt_pk_bf16_f32 v34, v46, v47
	v_cvt_pk_bf16_f32 v35, v48, v49
	v_cvt_pk_bf16_f32 v36, v42, v43
	v_cvt_pk_bf16_f32 v37, v44, v45
	global_store_dwordx4 v158, v[34:37], s[84:85] sc1
	s_waitcnt lgkmcnt(0)
; __device__ __forceinline__ unsigned cvt_pk_bf16(float lo, float hi) { unsigned r; asm volatile("v_cvt_pk_bf16_f32 %0, %1, %2" : "=v"(r) : "v"(lo), "v"(hi)); return r; }
;     __device__ __forceinline__ float silu(float x) const { return x * __builtin_amdgcn_rcpf(1.0f + __builtin_amdgcn_exp2f(-x * kLog2e)); }
; #define PG8_BAR __builtin_amdgcn_s_barrier()
;     __device__ __forceinline__ void operator()(const f32x4 (&acc)[2][2][4][2], const Unit& u, int wr, int wc, int fr, int fq) const {
;     ...
;             for (int m = 0; m < 4; ++m) {
;                 const int row = row0 + ai * HALF + m * 16;
;                 const float r = __builtin_amdgcn_rsqf(rr[ai][m] * (1.0f / 1024.0f) + 1e-6f);
;                 const f32x4 g0 = acc[ai][0][m][0] * r + bg0, g1 = acc[ai][0][m][1] * r + bg1, u0 = acc[ai][1][m][0] * r + bu0, u1 = acc[ai][1][m][1] * r + bu1;
;                 u32x4 w; w.x = cvt_pk_bf16(silu(g0[0]) * u0[0], silu(g0[1]) * u0[1]); w.y = cvt_pk_bf16(silu(g0[2]) * u0[2], silu(g0[3]) * u0[3]);
;                 w.z = cvt_pk_bf16(silu(g1[0]) * u1[0], silu(g1[1]) * u1[1]); w.w = cvt_pk_bf16(silu(g1[2]) * u1[2], silu(g1[3]) * u1[3]);
;                 *(u32x4*)(Aout + (size_t)row * 2816 + col0) = w;
; template <class Epi, class Sched, bool ALIGN_EPI = false, bool SP2 = false>
; __device__ __forceinline__ void gemm_phase(PG8_LAS unsigned char* lds, const Gemm g, const Sched& S, const Epi& E, const int tid) {
;     ...
;         if (!has_next) break;
; #pragma unroll
;         for (int a = 0; a < 2; ++a)
; #pragma unroll
;             for (int b = 0; b < 2; ++b)
; #pragma unroll
;                 for (int m = 0; m < 4; ++m)
; #pragma unroll
;                     for (int n = 0; n < 2; ++n) acc[a][b][m][n] = (f32x4){0.f, 0.f, 0.f, 0.f};
;         cur = nxt; cA = nA; cB = nB; ++ui;
;         if constexpr (ALIGN_EPI) { if (wr == 1) PG8_BAR; }
	v_add_f32_e32 v168, v176, v177
	v_add_f32_e32 v169, v178, v179
	v_add_f32_e32 v168, v168, v169
	v_fmamk_f32 v168, v168, 0x3a800000, v225
	v_rsq_f32_e32 v168, v168
	ds_read_b128 v[176:179], v159 offset:2816
	v_pk_fma_f32 v[30:31], v[30:31], v[168:169], v[78:79] op_sel_hi:[1,0,1]
	v_pk_fma_f32 v[32:33], v[32:33], v[168:169], v[80:81] op_sel_hi:[1,0,1]
	v_pk_fma_f32 v[26:27], v[26:27], v[168:169], v[70:71] op_sel_hi:[1,0,1]
	v_pk_fma_f32 v[28:29], v[28:29], v[168:169], v[72:73] op_sel_hi:[1,0,1]
	v_pk_fma_f32 v[22:23], v[22:23], v[168:169], v[66:67] op_sel_hi:[1,0,1]
	v_pk_fma_f32 v[24:25], v[24:25], v[168:169], v[68:69] op_sel_hi:[1,0,1]
	v_pk_fma_f32 v[18:19], v[18:19], v[168:169], v[62:63] op_sel_hi:[1,0,1]
	v_pk_fma_f32 v[20:21], v[20:21], v[168:169], v[64:65] op_sel_hi:[1,0,1]
	v_pk_mul_f32 v[170:171], v[30:31], s[2:3] op_sel_hi:[1,0]
	v_pk_mul_f32 v[172:173], v[32:33], s[2:3] op_sel_hi:[1,0]
	v_pk_mul_f32 v[174:175], v[26:27], s[2:3] op_sel_hi:[1,0]
	v_pk_mul_f32 v[180:181], v[28:29], s[2:3] op_sel_hi:[1,0]
	v_exp_f32_e32 v170, v170
	v_exp_f32_e32 v171, v171
	v_exp_f32_e32 v172, v172
	v_exp_f32_e32 v173, v173
	v_exp_f32_e32 v174, v174
	v_exp_f32_e32 v175, v175
	v_exp_f32_e32 v180, v180
	v_exp_f32_e32 v181, v181
	v_pk_add_f32 v[170:171], v[170:171], s[2:3] op_sel:[0,1] op_sel_hi:[1,1]
	v_pk_add_f32 v[172:173], v[172:173], s[2:3] op_sel:[0,1] op_sel_hi:[1,1]
	v_pk_add_f32 v[174:175], v[174:175], s[2:3] op_sel:[0,1] op_sel_hi:[1,1]
	v_pk_add_f32 v[180:181], v[180:181], s[2:3] op_sel:[0,1] op_sel_hi:[1,1]
	v_rcp_f32_e32 v170, v170
	v_rcp_f32_e32 v171, v171
	v_rcp_f32_e32 v172, v172
	v_rcp_f32_e32 v173, v173
	v_rcp_f32_e32 v174, v174
	v_rcp_f32_e32 v175, v175
	v_rcp_f32_e32 v180, v180
	v_rcp_f32_e32 v181, v181
	v_pk_mul_f32 v[30:31], v[30:31], v[170:171]
	v_pk_mul_f32 v[32:33], v[32:33], v[172:173]
	v_pk_mul_f32 v[26:27], v[26:27], v[174:175]
	v_pk_mul_f32 v[28:29], v[28:29], v[180:181]
	v_pk_mul_f32 v[30:31], v[22:23], v[30:31]
	v_pk_mul_f32 v[32:33], v[24:25], v[32:33]
	v_pk_mul_f32 v[26:27], v[18:19], v[26:27]
	v_pk_mul_f32 v[28:29], v[20:21], v[28:29]
	v_add_u32_e32 v158, 0xdc000, v167
	v_cvt_pk_bf16_f32 v18, v30, v31
	v_cvt_pk_bf16_f32 v19, v32, v33
	v_cvt_pk_bf16_f32 v20, v26, v27
	v_cvt_pk_bf16_f32 v21, v28, v29
	global_store_dwordx4 v158, v[18:21], s[84:85] sc1
	s_waitcnt lgkmcnt(0)
	v_add_f32_e32 v168, v176, v177
	v_add_f32_e32 v169, v178, v179
	v_add_f32_e32 v168, v168, v169
	v_fmamk_f32 v168, v168, 0x3a800000, v225
	v_rsq_f32_e32 v168, v168
	s_nop 0
	v_pk_fma_f32 v[14:15], v[14:15], v[168:169], v[78:79] op_sel_hi:[1,0,1]
	v_pk_fma_f32 v[16:17], v[16:17], v[168:169], v[80:81] op_sel_hi:[1,0,1]
	v_pk_fma_f32 v[10:11], v[10:11], v[168:169], v[70:71] op_sel_hi:[1,0,1]
	v_pk_fma_f32 v[12:13], v[12:13], v[168:169], v[72:73] op_sel_hi:[1,0,1]
	v_pk_fma_f32 v[6:7], v[6:7], v[168:169], v[66:67] op_sel_hi:[1,0,1]
	v_pk_fma_f32 v[8:9], v[8:9], v[168:169], v[68:69] op_sel_hi:[1,0,1]
	v_pk_fma_f32 v[2:3], v[2:3], v[168:169], v[62:63] op_sel_hi:[1,0,1]
	v_pk_fma_f32 v[4:5], v[4:5], v[168:169], v[64:65] op_sel_hi:[1,0,1]
	v_pk_mul_f32 v[170:171], v[14:15], s[2:3] op_sel_hi:[1,0]
	v_pk_mul_f32 v[172:173], v[16:17], s[2:3] op_sel_hi:[1,0]
	v_pk_mul_f32 v[174:175], v[10:11], s[2:3] op_sel_hi:[1,0]
	v_pk_mul_f32 v[180:181], v[12:13], s[2:3] op_sel_hi:[1,0]
	v_exp_f32_e32 v170, v170
	v_exp_f32_e32 v171, v171
	v_exp_f32_e32 v172, v172
	v_exp_f32_e32 v173, v173
	v_exp_f32_e32 v174, v174
	v_exp_f32_e32 v175, v175
	v_exp_f32_e32 v180, v180
	v_exp_f32_e32 v181, v181
	v_pk_add_f32 v[170:171], v[170:171], s[2:3] op_sel:[0,1] op_sel_hi:[1,1]
	v_pk_add_f32 v[172:173], v[172:173], s[2:3] op_sel:[0,1] op_sel_hi:[1,1]
	v_pk_add_f32 v[174:175], v[174:175], s[2:3] op_sel:[0,1] op_sel_hi:[1,1]
	v_pk_add_f32 v[180:181], v[180:181], s[2:3] op_sel:[0,1] op_sel_hi:[1,1]
	v_rcp_f32_e32 v170, v170
	v_rcp_f32_e32 v171, v171
	v_rcp_f32_e32 v172, v172
	v_rcp_f32_e32 v173, v173
	v_rcp_f32_e32 v174, v174
	v_rcp_f32_e32 v175, v175
	v_rcp_f32_e32 v180, v180
	v_rcp_f32_e32 v181, v181
	v_pk_mul_f32 v[14:15], v[14:15], v[170:171]
	v_pk_mul_f32 v[16:17], v[16:17], v[172:173]
	v_pk_mul_f32 v[10:11], v[10:11], v[174:175]
	v_pk_mul_f32 v[12:13], v[12:13], v[180:181]
	v_pk_mul_f32 v[14:15], v[6:7], v[14:15]
	v_pk_mul_f32 v[16:17], v[8:9], v[16:17]
	v_pk_mul_f32 v[10:11], v[2:3], v[10:11]
	v_pk_mul_f32 v[12:13], v[4:5], v[12:13]
	v_add_u32_e32 v158, 0xf2000, v167
	v_cvt_pk_bf16_f32 v2, v14, v15
	v_cvt_pk_bf16_f32 v3, v16, v17
	v_cvt_pk_bf16_f32 v4, v10, v11
	v_cvt_pk_bf16_f32 v5, v12, v13
	global_store_dwordx4 v158, v[2:5], s[84:85] sc1
	s_andn2_b64 vcc, exec, s[0:1]
	s_mov_b64 s[2:3], -1
	s_cbranch_vccnz .LBB0_58
	s_andn2_b64 vcc, exec, s[70:71]
	s_cbranch_vccnz .LBB0_57
	s_barrier
	s_branch .LBB0_57
